# accumulator zeroing per GEMM tile with v_mov_b64 (half the VALU instructions)
# speedup vs baseline: 1.0096x; 1.0031x over previous
.LBB0_161:
	s_add_u32 s86, s69, s6
	s_addc_u32 s87, s70, s7
	s_add_u32 s88, s71, s8
	s_addc_u32 s89, s72, s9
	s_ashr_i32 s23, s22, 31
	s_lshl_b64 s[6:7], s[22:23], 19
	s_add_u32 s24, s34, s6
	s_addc_u32 s25, s35, s7
	s_and_b64 s[8:9], s[0:1], exec
	s_cselect_b32 s23, s25, s43
	s_cselect_b32 s90, s24, s42
	s_ashr_i32 s21, s20, 31
	s_lshl_b64 s[8:9], s[20:21], 19
	s_add_u32 s26, s17, s8
	s_addc_u32 s27, s19, s9
	s_and_b64 s[48:49], s[0:1], exec
	s_cselect_b32 s21, s27, s39
	s_cselect_b32 s91, s26, s38
	s_add_u32 s48, s90, 0x80
	s_addc_u32 s49, s23, 0
	s_add_u32 s54, s91, 0x80
	v_mov_b32_e32 v0, 0
	s_addc_u32 s55, s21, 0
	v_lshl_add_u64 v[128:129], s[42:43], 0, v[150:151]
	v_lshl_add_u64 v[130:131], s[42:43], 0, v[152:153]
	s_mov_b32 s92, 0
	s_mov_b64 s[56:57], 0
	v_mov_b32_e32 v1, v0
	v_mov_b64_e32 v[2:3], 0
	v_mov_b64_e32 v[4:5], 0
	v_mov_b64_e32 v[6:7], 0
	v_mov_b64_e32 v[16:17], 0
	v_mov_b64_e32 v[18:19], 0
	v_mov_b64_e32 v[20:21], 0
	v_mov_b64_e32 v[22:23], 0
	v_mov_b64_e32 v[32:33], 0
	v_mov_b64_e32 v[34:35], 0
	v_mov_b64_e32 v[36:37], 0
	v_mov_b64_e32 v[38:39], 0
	v_mov_b64_e32 v[48:49], 0
	v_mov_b64_e32 v[50:51], 0
	v_mov_b64_e32 v[52:53], 0
	v_mov_b64_e32 v[54:55], 0
	v_mov_b64_e32 v[8:9], 0
	v_mov_b64_e32 v[10:11], 0
	v_mov_b64_e32 v[12:13], 0
	v_mov_b64_e32 v[14:15], 0
	v_mov_b64_e32 v[24:25], 0
	v_mov_b64_e32 v[26:27], 0
	v_mov_b64_e32 v[28:29], 0
	v_mov_b64_e32 v[30:31], 0
	v_mov_b64_e32 v[40:41], 0
	v_mov_b64_e32 v[42:43], 0
	v_mov_b64_e32 v[44:45], 0
	v_mov_b64_e32 v[46:47], 0
	v_mov_b64_e32 v[56:57], 0
	v_mov_b64_e32 v[58:59], 0
	v_mov_b64_e32 v[60:61], 0
	v_mov_b64_e32 v[62:63], 0
	v_mov_b64_e32 v[64:65], 0
	v_mov_b64_e32 v[66:67], 0
	v_mov_b64_e32 v[68:69], 0
	v_mov_b64_e32 v[70:71], 0
	v_mov_b64_e32 v[80:81], 0
	v_mov_b64_e32 v[82:83], 0
	v_mov_b64_e32 v[84:85], 0
	v_mov_b64_e32 v[86:87], 0
	v_mov_b64_e32 v[96:97], 0
	v_mov_b64_e32 v[98:99], 0
	v_mov_b64_e32 v[100:101], 0
	v_mov_b64_e32 v[102:103], 0
	v_mov_b64_e32 v[112:113], 0
	v_mov_b64_e32 v[114:115], 0
	v_mov_b64_e32 v[116:117], 0
	v_mov_b64_e32 v[118:119], 0
	v_mov_b64_e32 v[72:73], 0
	v_mov_b64_e32 v[74:75], 0
	v_mov_b64_e32 v[76:77], 0
	v_mov_b64_e32 v[78:79], 0
	v_mov_b64_e32 v[88:89], 0
	v_mov_b64_e32 v[90:91], 0
	v_mov_b64_e32 v[92:93], 0
	v_mov_b64_e32 v[94:95], 0
	v_mov_b64_e32 v[104:105], 0
	v_mov_b64_e32 v[106:107], 0
	v_mov_b64_e32 v[108:109], 0
	v_mov_b64_e32 v[110:111], 0
	v_mov_b64_e32 v[120:121], 0
	v_mov_b64_e32 v[122:123], 0
	v_mov_b64_e32 v[124:125], 0
	v_mov_b64_e32 v[126:127], 0
	s_branch .LBB0_163

.LBB0_611:
	s_add_u32 s84, s66, s30
	s_addc_u32 s85, s67, s31
	s_add_u32 s86, s68, s6
	s_addc_u32 s87, s69, s7
	s_ashr_i32 s19, s18, 31
	s_lshl_b64 s[6:7], s[18:19], 18
	s_add_u32 s24, s58, s6
	s_addc_u32 s25, s59, s7
	s_and_b64 s[4:5], s[4:5], exec
	s_cselect_b32 s39, s25, s27
	s_cselect_b32 s38, s24, s26
	s_add_u32 s44, s20, 0x80
	s_addc_u32 s45, s21, 0
	s_add_u32 s46, s38, 0x80
	s_addc_u32 s47, s39, 0
	s_lshl_b32 s30, s8, 8
	s_lshl_b32 s19, s48, 8
	s_ashr_i32 s31, s30, 31
	v_mov_b32_e32 v0, 0
	v_mov_b32_e32 v153, s31
	v_or_b32_e32 v152, s30, v144
	s_or_b32 s88, s19, 16
	s_or_b32 s89, s19, 32
	s_or_b32 s90, s19, 48
	s_or_b32 s91, s19, 0x80
	s_or_b32 s92, s19, 0x90
	s_or_b32 s93, s19, 0xa0
	s_or_b32 s94, s19, 0xb0
	s_mov_b32 s95, 0
	s_mov_b64 s[48:49], 0
	v_mov_b32_e32 v1, v0
	v_mov_b64_e32 v[2:3], 0
	v_mov_b64_e32 v[4:5], 0
	v_mov_b64_e32 v[6:7], 0
	v_mov_b64_e32 v[12:13], 0
	v_mov_b64_e32 v[14:15], 0
	v_mov_b64_e32 v[20:21], 0
	v_mov_b64_e32 v[22:23], 0
	v_mov_b64_e32 v[28:29], 0
	v_mov_b64_e32 v[30:31], 0
	v_mov_b64_e32 v[36:37], 0
	v_mov_b64_e32 v[38:39], 0
	v_mov_b64_e32 v[44:45], 0
	v_mov_b64_e32 v[46:47], 0
	v_mov_b64_e32 v[52:53], 0
	v_mov_b64_e32 v[54:55], 0
	v_mov_b64_e32 v[8:9], 0
	v_mov_b64_e32 v[10:11], 0
	v_mov_b64_e32 v[16:17], 0
	v_mov_b64_e32 v[18:19], 0
	v_mov_b64_e32 v[24:25], 0
	v_mov_b64_e32 v[26:27], 0
	v_mov_b64_e32 v[32:33], 0
	v_mov_b64_e32 v[34:35], 0
	v_mov_b64_e32 v[40:41], 0
	v_mov_b64_e32 v[42:43], 0
	v_mov_b64_e32 v[48:49], 0
	v_mov_b64_e32 v[50:51], 0
	v_mov_b64_e32 v[56:57], 0
	v_mov_b64_e32 v[58:59], 0
	v_mov_b64_e32 v[60:61], 0
	v_mov_b64_e32 v[62:63], 0
	v_mov_b64_e32 v[64:65], 0
	v_mov_b64_e32 v[66:67], 0
	v_mov_b64_e32 v[68:69], 0
	v_mov_b64_e32 v[70:71], 0
	v_mov_b64_e32 v[76:77], 0
	v_mov_b64_e32 v[78:79], 0
	v_mov_b64_e32 v[84:85], 0
	v_mov_b64_e32 v[86:87], 0
	v_mov_b64_e32 v[92:93], 0
	v_mov_b64_e32 v[94:95], 0
	v_mov_b64_e32 v[100:101], 0
	v_mov_b64_e32 v[102:103], 0
	v_mov_b64_e32 v[108:109], 0
	v_mov_b64_e32 v[110:111], 0
	v_mov_b64_e32 v[116:117], 0
	v_mov_b64_e32 v[118:119], 0
	v_mov_b64_e32 v[72:73], 0
	v_mov_b64_e32 v[74:75], 0
	v_mov_b64_e32 v[80:81], 0
	v_mov_b64_e32 v[82:83], 0
	v_mov_b64_e32 v[88:89], 0
	v_mov_b64_e32 v[90:91], 0
	v_mov_b64_e32 v[96:97], 0
	v_mov_b64_e32 v[98:99], 0
	v_mov_b64_e32 v[104:105], 0
	v_mov_b64_e32 v[106:107], 0
	v_mov_b64_e32 v[112:113], 0
	v_mov_b64_e32 v[114:115], 0
	v_mov_b64_e32 v[120:121], 0
	v_mov_b64_e32 v[122:123], 0
	v_mov_b64_e32 v[124:125], 0
	v_mov_b64_e32 v[126:127], 0
	s_branch .LBB0_613

.LBB0_713:
	s_add_u32 s19, s63, s6
	s_addc_u32 s29, s64, s7
	s_add_u32 s31, s65, s8
	s_addc_u32 s79, s66, s9
	s_ashr_i32 s23, s22, 31
	s_lshl_b64 s[6:7], s[22:23], 19
	s_add_u32 s24, s34, s6
	s_addc_u32 s25, s35, s7
	s_and_b64 s[8:9], s[4:5], exec
	s_cselect_b32 s23, s25, s45
	s_cselect_b32 s80, s24, s44
	s_ashr_i32 s21, s20, 31
	s_lshl_b64 s[8:9], s[20:21], 19
	s_add_u32 s26, s42, s8
	s_addc_u32 s27, s43, s9
	s_and_b64 s[36:37], s[4:5], exec
	s_cselect_b32 s21, s27, s39
	s_cselect_b32 s81, s26, s38
	s_add_u32 s36, s80, 0x80
	s_addc_u32 s37, s23, 0
	s_add_u32 s46, s81, 0x80
	v_mov_b32_e32 v0, 0
	s_addc_u32 s47, s21, 0
	v_lshl_add_u64 v[128:129], s[44:45], 0, v[156:157]
	v_lshl_add_u64 v[130:131], s[44:45], 0, v[158:159]
	s_mov_b32 s82, 0
	s_mov_b64 s[48:49], 0
	v_mov_b32_e32 v1, v0
	v_mov_b64_e32 v[2:3], 0
	v_mov_b64_e32 v[4:5], 0
	v_mov_b64_e32 v[6:7], 0
	v_mov_b64_e32 v[16:17], 0
	v_mov_b64_e32 v[18:19], 0
	v_mov_b64_e32 v[20:21], 0
	v_mov_b64_e32 v[22:23], 0
	v_mov_b64_e32 v[32:33], 0
	v_mov_b64_e32 v[34:35], 0
	v_mov_b64_e32 v[36:37], 0
	v_mov_b64_e32 v[38:39], 0
	v_mov_b64_e32 v[48:49], 0
	v_mov_b64_e32 v[50:51], 0
	v_mov_b64_e32 v[52:53], 0
	v_mov_b64_e32 v[54:55], 0
	v_mov_b64_e32 v[8:9], 0
	v_mov_b64_e32 v[10:11], 0
	v_mov_b64_e32 v[12:13], 0
	v_mov_b64_e32 v[14:15], 0
	v_mov_b64_e32 v[24:25], 0
	v_mov_b64_e32 v[26:27], 0
	v_mov_b64_e32 v[28:29], 0
	v_mov_b64_e32 v[30:31], 0
	v_mov_b64_e32 v[40:41], 0
	v_mov_b64_e32 v[42:43], 0
	v_mov_b64_e32 v[44:45], 0
	v_mov_b64_e32 v[46:47], 0
	v_mov_b64_e32 v[56:57], 0
	v_mov_b64_e32 v[58:59], 0
	v_mov_b64_e32 v[60:61], 0
	v_mov_b64_e32 v[62:63], 0
	v_mov_b64_e32 v[64:65], 0
	v_mov_b64_e32 v[66:67], 0
	v_mov_b64_e32 v[68:69], 0
	v_mov_b64_e32 v[70:71], 0
	v_mov_b64_e32 v[80:81], 0
	v_mov_b64_e32 v[82:83], 0
	v_mov_b64_e32 v[84:85], 0
	v_mov_b64_e32 v[86:87], 0
	v_mov_b64_e32 v[96:97], 0
	v_mov_b64_e32 v[98:99], 0
	v_mov_b64_e32 v[100:101], 0
	v_mov_b64_e32 v[102:103], 0
	v_mov_b64_e32 v[112:113], 0
	v_mov_b64_e32 v[114:115], 0
	v_mov_b64_e32 v[116:117], 0
	v_mov_b64_e32 v[118:119], 0
	v_mov_b64_e32 v[72:73], 0
	v_mov_b64_e32 v[74:75], 0
	v_mov_b64_e32 v[76:77], 0
	v_mov_b64_e32 v[78:79], 0
	v_mov_b64_e32 v[88:89], 0
	v_mov_b64_e32 v[90:91], 0
	v_mov_b64_e32 v[92:93], 0
	v_mov_b64_e32 v[94:95], 0
	v_mov_b64_e32 v[104:105], 0
	v_mov_b64_e32 v[106:107], 0
	v_mov_b64_e32 v[108:109], 0
	v_mov_b64_e32 v[110:111], 0
	v_mov_b64_e32 v[120:121], 0
	v_mov_b64_e32 v[122:123], 0
	v_mov_b64_e32 v[124:125], 0
	v_mov_b64_e32 v[126:127], 0
	s_branch .LBB0_715

.LBB0_805:
	s_add_u32 s27, s61, s4
	s_addc_u32 s72, s62, s5
	s_add_u32 s73, s63, s6
	s_addc_u32 s78, s64, s7
	s_ashr_i32 s21, s20, 31
	s_lshl_b64 s[4:5], s[20:21], 19
	s_add_u32 s22, s40, s4
	s_addc_u32 s23, s41, s5
	s_and_b64 s[6:7], s[0:1], exec
	s_cselect_b32 s21, s23, s31
	s_cselect_b32 s79, s22, s30
	s_ashr_i32 s19, s18, 31
	s_lshl_b64 s[6:7], s[18:19], 19
	s_add_u32 s24, s42, s6
	s_addc_u32 s25, s43, s7
	s_and_b64 s[36:37], s[0:1], exec
	s_cselect_b32 s19, s25, s29
	s_cselect_b32 s80, s24, s28
	s_add_u32 s36, s79, 0x80
	s_addc_u32 s37, s21, 0
	s_add_u32 s38, s80, 0x80
	v_mov_b32_e32 v0, 0
	s_addc_u32 s39, s19, 0
	v_lshl_add_u64 v[148:149], s[30:31], 0, v[140:141]
	v_lshl_add_u64 v[150:151], s[30:31], 0, v[142:143]
	s_mov_b32 s81, 0
	s_mov_b64 s[44:45], 0
	v_mov_b32_e32 v1, v0
	v_mov_b64_e32 v[2:3], 0
	v_mov_b64_e32 v[4:5], 0
	v_mov_b64_e32 v[6:7], 0
	v_mov_b64_e32 v[16:17], 0
	v_mov_b64_e32 v[18:19], 0
	v_mov_b64_e32 v[20:21], 0
	v_mov_b64_e32 v[22:23], 0
	v_mov_b64_e32 v[32:33], 0
	v_mov_b64_e32 v[34:35], 0
	v_mov_b64_e32 v[36:37], 0
	v_mov_b64_e32 v[38:39], 0
	v_mov_b64_e32 v[48:49], 0
	v_mov_b64_e32 v[50:51], 0
	v_mov_b64_e32 v[52:53], 0
	v_mov_b64_e32 v[54:55], 0
	v_mov_b64_e32 v[8:9], 0
	v_mov_b64_e32 v[10:11], 0
	v_mov_b64_e32 v[12:13], 0
	v_mov_b64_e32 v[14:15], 0
	v_mov_b64_e32 v[24:25], 0
	v_mov_b64_e32 v[26:27], 0
	v_mov_b64_e32 v[28:29], 0
	v_mov_b64_e32 v[30:31], 0
	v_mov_b64_e32 v[40:41], 0
	v_mov_b64_e32 v[42:43], 0
	v_mov_b64_e32 v[44:45], 0
	v_mov_b64_e32 v[46:47], 0
	v_mov_b64_e32 v[56:57], 0
	v_mov_b64_e32 v[58:59], 0
	v_mov_b64_e32 v[60:61], 0
	v_mov_b64_e32 v[62:63], 0
	v_mov_b64_e32 v[64:65], 0
	v_mov_b64_e32 v[66:67], 0
	v_mov_b64_e32 v[68:69], 0
	v_mov_b64_e32 v[70:71], 0
	v_mov_b64_e32 v[80:81], 0
	v_mov_b64_e32 v[82:83], 0
	v_mov_b64_e32 v[84:85], 0
	v_mov_b64_e32 v[86:87], 0
	v_mov_b64_e32 v[96:97], 0
	v_mov_b64_e32 v[98:99], 0
	v_mov_b64_e32 v[100:101], 0
	v_mov_b64_e32 v[102:103], 0
	v_mov_b64_e32 v[112:113], 0
	v_mov_b64_e32 v[114:115], 0
	v_mov_b64_e32 v[116:117], 0
	v_mov_b64_e32 v[118:119], 0
	v_mov_b64_e32 v[72:73], 0
	v_mov_b64_e32 v[74:75], 0
	v_mov_b64_e32 v[76:77], 0
	v_mov_b64_e32 v[78:79], 0
	v_mov_b64_e32 v[88:89], 0
	v_mov_b64_e32 v[90:91], 0
	v_mov_b64_e32 v[92:93], 0
	v_mov_b64_e32 v[94:95], 0
	v_mov_b64_e32 v[104:105], 0
	v_mov_b64_e32 v[106:107], 0
	v_mov_b64_e32 v[108:109], 0
	v_mov_b64_e32 v[110:111], 0
	v_mov_b64_e32 v[120:121], 0
	v_mov_b64_e32 v[122:123], 0
	v_mov_b64_e32 v[124:125], 0
	v_mov_b64_e32 v[126:127], 0
	s_branch .LBB0_807

.LBB0_895:
	s_add_u32 s70, s55, s28
	s_addc_u32 s71, s56, s29
	s_add_u32 s72, s57, s30
	s_addc_u32 s73, s58, s31
	s_add_u32 s28, s4, 0x80
	s_addc_u32 s29, s5, 0
	s_add_u32 s30, s20, 0x80
	v_mov_b32_e32 v0, 0
	s_addc_u32 s31, s21, 0
	v_lshl_add_u64 v[128:129], s[26:27], 0, v[148:149]
	v_lshl_add_u64 v[130:131], s[26:27], 0, v[150:151]
	s_mov_b32 s78, 0
	s_mov_b64 s[36:37], 0
	v_mov_b32_e32 v1, v0
	v_mov_b64_e32 v[2:3], 0
	v_mov_b64_e32 v[4:5], 0
	v_mov_b64_e32 v[6:7], 0
	v_mov_b64_e32 v[16:17], 0
	v_mov_b64_e32 v[18:19], 0
	v_mov_b64_e32 v[20:21], 0
	v_mov_b64_e32 v[22:23], 0
	v_mov_b64_e32 v[32:33], 0
	v_mov_b64_e32 v[34:35], 0
	v_mov_b64_e32 v[36:37], 0
	v_mov_b64_e32 v[38:39], 0
	v_mov_b64_e32 v[48:49], 0
	v_mov_b64_e32 v[50:51], 0
	v_mov_b64_e32 v[52:53], 0
	v_mov_b64_e32 v[54:55], 0
	v_mov_b64_e32 v[8:9], 0
	v_mov_b64_e32 v[10:11], 0
	v_mov_b64_e32 v[12:13], 0
	v_mov_b64_e32 v[14:15], 0
	v_mov_b64_e32 v[24:25], 0
	v_mov_b64_e32 v[26:27], 0
	v_mov_b64_e32 v[28:29], 0
	v_mov_b64_e32 v[30:31], 0
	v_mov_b64_e32 v[40:41], 0
	v_mov_b64_e32 v[42:43], 0
	v_mov_b64_e32 v[44:45], 0
	v_mov_b64_e32 v[46:47], 0
	v_mov_b64_e32 v[56:57], 0
	v_mov_b64_e32 v[58:59], 0
	v_mov_b64_e32 v[60:61], 0
	v_mov_b64_e32 v[62:63], 0
	v_mov_b64_e32 v[64:65], 0
	v_mov_b64_e32 v[66:67], 0
	v_mov_b64_e32 v[68:69], 0
	v_mov_b64_e32 v[70:71], 0
	v_mov_b64_e32 v[80:81], 0
	v_mov_b64_e32 v[82:83], 0
	v_mov_b64_e32 v[84:85], 0
	v_mov_b64_e32 v[86:87], 0
	v_mov_b64_e32 v[96:97], 0
	v_mov_b64_e32 v[98:99], 0
	v_mov_b64_e32 v[100:101], 0
	v_mov_b64_e32 v[102:103], 0
	v_mov_b64_e32 v[112:113], 0
	v_mov_b64_e32 v[114:115], 0
	v_mov_b64_e32 v[116:117], 0
	v_mov_b64_e32 v[118:119], 0
	v_mov_b64_e32 v[72:73], 0
	v_mov_b64_e32 v[74:75], 0
	v_mov_b64_e32 v[76:77], 0
	v_mov_b64_e32 v[78:79], 0
	v_mov_b64_e32 v[88:89], 0
	v_mov_b64_e32 v[90:91], 0
	v_mov_b64_e32 v[92:93], 0
	v_mov_b64_e32 v[94:95], 0
	v_mov_b64_e32 v[104:105], 0
	v_mov_b64_e32 v[106:107], 0
	v_mov_b64_e32 v[108:109], 0
	v_mov_b64_e32 v[110:111], 0
	v_mov_b64_e32 v[120:121], 0
	v_mov_b64_e32 v[122:123], 0
	v_mov_b64_e32 v[124:125], 0
	v_mov_b64_e32 v[126:127], 0
	s_branch .LBB0_897

.LBB0_1017:
	s_add_u32 s65, s54, s6
	s_addc_u32 s66, s55, s7
	s_add_u32 s67, s56, s8
	s_addc_u32 s68, s57, s9
	s_ashr_i32 s19, s18, 31
	s_lshl_b64 s[6:7], s[18:19], 19
	s_add_u32 s20, s34, s6
	s_addc_u32 s21, s35, s7
	s_and_b64 s[8:9], s[0:1], exec
	s_cselect_b32 s19, s21, s29
	s_cselect_b32 s69, s20, s28
	s_ashr_i32 s17, s16, 31
	s_lshl_b64 s[8:9], s[16:17], 19
	s_add_u32 s22, s48, s8
	s_addc_u32 s23, s49, s9
	s_and_b64 s[30:31], s[0:1], exec
	s_cselect_b32 s17, s23, s27
	s_cselect_b32 s70, s22, s26
	s_add_u32 s30, s69, 0x80
	s_addc_u32 s31, s19, 0
	s_add_u32 s36, s70, 0x80
	v_mov_b32_e32 v0, 0
	s_addc_u32 s37, s17, 0
	v_lshl_add_u64 v[128:129], s[28:29], 0, v[196:197]
	v_lshl_add_u64 v[130:131], s[28:29], 0, v[198:199]
	s_mov_b32 s71, 0
	s_mov_b64 s[38:39], 0
	v_mov_b32_e32 v1, v0
	v_mov_b64_e32 v[2:3], 0
	v_mov_b64_e32 v[4:5], 0
	v_mov_b64_e32 v[6:7], 0
	v_mov_b64_e32 v[16:17], 0
	v_mov_b64_e32 v[18:19], 0
	v_mov_b64_e32 v[20:21], 0
	v_mov_b64_e32 v[22:23], 0
	v_mov_b64_e32 v[32:33], 0
	v_mov_b64_e32 v[34:35], 0
	v_mov_b64_e32 v[36:37], 0
	v_mov_b64_e32 v[38:39], 0
	v_mov_b64_e32 v[48:49], 0
	v_mov_b64_e32 v[50:51], 0
	v_mov_b64_e32 v[52:53], 0
	v_mov_b64_e32 v[54:55], 0
	v_mov_b64_e32 v[8:9], 0
	v_mov_b64_e32 v[10:11], 0
	v_mov_b64_e32 v[12:13], 0
	v_mov_b64_e32 v[14:15], 0
	v_mov_b64_e32 v[24:25], 0
	v_mov_b64_e32 v[26:27], 0
	v_mov_b64_e32 v[28:29], 0
	v_mov_b64_e32 v[30:31], 0
	v_mov_b64_e32 v[40:41], 0
	v_mov_b64_e32 v[42:43], 0
	v_mov_b64_e32 v[44:45], 0
	v_mov_b64_e32 v[46:47], 0
	v_mov_b64_e32 v[56:57], 0
	v_mov_b64_e32 v[58:59], 0
	v_mov_b64_e32 v[60:61], 0
	v_mov_b64_e32 v[62:63], 0
	v_mov_b64_e32 v[64:65], 0
	v_mov_b64_e32 v[66:67], 0
	v_mov_b64_e32 v[68:69], 0
	v_mov_b64_e32 v[70:71], 0
	v_mov_b64_e32 v[80:81], 0
	v_mov_b64_e32 v[82:83], 0
	v_mov_b64_e32 v[84:85], 0
	v_mov_b64_e32 v[86:87], 0
	v_mov_b64_e32 v[96:97], 0
	v_mov_b64_e32 v[98:99], 0
	v_mov_b64_e32 v[100:101], 0
	v_mov_b64_e32 v[102:103], 0
	v_mov_b64_e32 v[112:113], 0
	v_mov_b64_e32 v[114:115], 0
	v_mov_b64_e32 v[116:117], 0
	v_mov_b64_e32 v[118:119], 0
	v_mov_b64_e32 v[72:73], 0
	v_mov_b64_e32 v[74:75], 0
	v_mov_b64_e32 v[76:77], 0
	v_mov_b64_e32 v[78:79], 0
	v_mov_b64_e32 v[88:89], 0
	v_mov_b64_e32 v[90:91], 0
	v_mov_b64_e32 v[92:93], 0
	v_mov_b64_e32 v[94:95], 0
	v_mov_b64_e32 v[104:105], 0
	v_mov_b64_e32 v[106:107], 0
	v_mov_b64_e32 v[108:109], 0
	v_mov_b64_e32 v[110:111], 0
	v_mov_b64_e32 v[120:121], 0
	v_mov_b64_e32 v[122:123], 0
	v_mov_b64_e32 v[124:125], 0
	v_mov_b64_e32 v[126:127], 0
	s_branch .LBB0_1019
